# adds: restore barrier moved after next-unit arithmetic in all 4 GEMM instances; G2/WOUT tile-order arithmetic with gsz=8 shift/mask
# speedup vs baseline: 1.0035x; 1.0035x over previous
.LBB0_325:
	s_ashr_i32 s17, s17, 3
	s_add_i32 s17, s37, s17
	s_ashr_i32 s34, s17, 31
	s_lshr_b32 s34, s34, 27
	s_add_i32 s34, s17, s34
	s_ashr_i32 s35, s34, 5
	s_lshl_b32 s35, s35, 3
	s_andn2_b32 s34, s34, 31
	s_sub_i32 s34, s17, s34
	s_lshr_b32 s17, s34, 3
	s_and_b32 s34, s34, 7
	s_add_i32 s77, s35, s34

.LBB0_330:
	s_add_u32 s42, s56, 0x80
	s_addc_u32 s43, s57, 0
	s_add_u32 s56, s48, 0x100
	s_addc_u32 s57, s49, 0
	s_mov_b32 s48, 0
	s_cmp_lt_u32 s75, 2
	s_cbranch_scc1 .Lrb331_skip
	s_andn2_b64 vcc, exec, s[20:21]
	s_cbranch_vccnz .Lrb331_skip
	s_barrier
.Lrb331_skip:
	s_add_i32 s80, s48, 2
	s_add_u32 s81, s42, 0x80
	s_addc_u32 s49, s43, 0
	s_add_i32 s84, 0, 0x10000
	s_cmp_eq_u32 s74, s48
	s_cselect_b32 s49, s35, s49
	s_cselect_b32 s48, s34, s81
	s_cselect_b32 s87, s37, s57
	s_cselect_b32 s86, s36, s56
	s_add_i32 s81, 0, 0x14000
	v_add_u32_e32 v142, s84, v186
	v_add_u32_e32 v170, s81, v186
	ds_read_b128 v[130:133], v142
	ds_read_b128 v[134:137], v142 offset:1024
	ds_read_b128 v[138:141], v142 offset:2048
	ds_read_b128 v[142:145], v142 offset:3072
	ds_read_b128 v[146:149], v170
	ds_read_b128 v[150:153], v170 offset:1024
	ds_read_b128 v[154:157], v170 offset:2048
	ds_read_b128 v[170:173], v170 offset:3072
	v_lshl_add_u64 v[210:211], s[42:43], 0, v[164:165]
	s_add_i32 m0, s45, 0xc000
	ds_read_b128 v[174:177], v188
	ds_read_b128 v[178:181], v188 offset:1024
	ds_read_b128 v[182:185], v188 offset:2048
	ds_read_b128 v[190:193], v188 offset:3072
	ds_read_b128 v[194:197], v188 offset:4096
	ds_read_b128 v[198:201], v188 offset:5120
	ds_read_b128 v[202:205], v188 offset:6144
	ds_read_b128 v[206:209], v188 offset:7168
	global_load_lds_dwordx4 v[210:211], off
	v_lshl_add_u64 v[210:211], s[42:43], 0, v[168:169]
	s_add_i32 m0, s45, 0xe000
	s_nop 0
	global_load_lds_dwordx4 v[210:211], off
	s_waitcnt vmcnt(8)
	s_waitcnt lgkmcnt(0)
	s_barrier
	s_setprio 1
	s_waitcnt lgkmcnt(0)
	v_mfma_f32_16x16x32_bf16 v[126:129], v[130:133], v[174:177], 0
	v_mfma_f32_16x16x32_bf16 v[122:125], v[138:141], v[174:177], 0
	v_mfma_f32_16x16x32_bf16 v[110:113], v[130:133], v[182:185], 0
	v_mfma_f32_16x16x32_bf16 v[106:109], v[138:141], v[182:185], 0
	v_mfma_f32_16x16x32_bf16 v[92:95], v[130:133], v[194:197], 0
	v_mfma_f32_16x16x32_bf16 v[88:91], v[138:141], v[194:197], 0
	v_mfma_f32_16x16x32_bf16 v[76:79], v[130:133], v[202:205], 0
	v_mfma_f32_16x16x32_bf16 v[72:75], v[138:141], v[202:205], 0
	v_mfma_f32_16x16x32_bf16 v[126:129], v[134:137], v[178:181], v[126:129]
	v_mfma_f32_16x16x32_bf16 v[122:125], v[142:145], v[178:181], v[122:125]
	v_mfma_f32_16x16x32_bf16 v[110:113], v[134:137], v[190:193], v[110:113]
	v_mfma_f32_16x16x32_bf16 v[106:109], v[142:145], v[190:193], v[106:109]
	v_mfma_f32_16x16x32_bf16 v[92:95], v[134:137], v[198:201], v[92:95]
	v_mfma_f32_16x16x32_bf16 v[88:91], v[142:145], v[198:201], v[88:91]
	v_mfma_f32_16x16x32_bf16 v[76:79], v[134:137], v[206:209], v[76:79]
	v_mfma_f32_16x16x32_bf16 v[72:75], v[142:145], v[206:209], v[72:75]
	v_mfma_f32_16x16x32_bf16 v[118:121], v[146:149], v[174:177], 0
	v_mfma_f32_16x16x32_bf16 v[114:117], v[154:157], v[174:177], 0
	v_mfma_f32_16x16x32_bf16 v[102:105], v[146:149], v[182:185], 0
	v_mfma_f32_16x16x32_bf16 v[98:101], v[154:157], v[182:185], 0
	v_mfma_f32_16x16x32_bf16 v[84:87], v[146:149], v[194:197], 0
	v_mfma_f32_16x16x32_bf16 v[80:83], v[154:157], v[194:197], 0
	v_mfma_f32_16x16x32_bf16 v[68:71], v[146:149], v[202:205], 0
	v_mfma_f32_16x16x32_bf16 v[64:67], v[154:157], v[202:205], 0
	v_mfma_f32_16x16x32_bf16 v[118:121], v[150:153], v[178:181], v[118:121]
	v_mfma_f32_16x16x32_bf16 v[114:117], v[170:173], v[178:181], v[114:117]
	v_mfma_f32_16x16x32_bf16 v[102:105], v[150:153], v[190:193], v[102:105]
	v_mfma_f32_16x16x32_bf16 v[98:101], v[170:173], v[190:193], v[98:101]
	v_mfma_f32_16x16x32_bf16 v[84:87], v[150:153], v[198:201], v[84:87]
	v_mfma_f32_16x16x32_bf16 v[80:83], v[170:173], v[198:201], v[80:83]
	v_mfma_f32_16x16x32_bf16 v[68:71], v[150:153], v[206:209], v[68:71]
	v_mfma_f32_16x16x32_bf16 v[64:67], v[170:173], v[206:209], v[64:67]
	s_setprio 0
	s_barrier
	s_add_i32 s84, s84, s8
	v_lshl_add_u64 v[210:211], s[86:87], 0, v[96:97]
	s_mov_b32 m0, s84
	ds_read_b128 v[174:177], v188 offset:16384
	ds_read_b128 v[178:181], v188 offset:17408
	ds_read_b128 v[182:185], v188 offset:18432
	ds_read_b128 v[190:193], v188 offset:19456
	ds_read_b128 v[194:197], v188 offset:20480
	ds_read_b128 v[198:201], v188 offset:21504
	ds_read_b128 v[202:205], v188 offset:22528
	ds_read_b128 v[206:209], v188 offset:23552
	global_load_lds_dwordx4 v[210:211], off
	s_add_i32 m0, s84, 0x2000
	v_lshl_add_u64 v[212:213], s[86:87], 0, v[162:163]
	s_add_u32 s86, s86, s16
	s_addc_u32 s87, s87, 0
	s_add_i32 s81, s81, s8
	global_load_lds_dwordx4 v[212:213], off
	v_lshl_add_u64 v[216:217], s[86:87], 0, v[96:97]
	s_mov_b32 m0, s81
	v_lshl_add_u64 v[218:219], s[86:87], 0, v[162:163]
	global_load_lds_dwordx4 v[216:217], off
	s_add_i32 m0, s81, 0x2000
	v_lshl_add_u64 v[220:221], s[48:49], 0, v[158:159]
	global_load_lds_dwordx4 v[218:219], off
	s_mov_b32 m0, s45
	v_lshl_add_u64 v[222:223], s[48:49], 0, v[160:161]
	global_load_lds_dwordx4 v[220:221], off
	s_mov_b32 m0, s55
	s_nop 0
	global_load_lds_dwordx4 v[222:223], off
	s_waitcnt vmcnt(8)
	s_waitcnt lgkmcnt(0)
	s_barrier
	s_setprio 1
	s_waitcnt lgkmcnt(0)
	v_mfma_f32_16x16x32_bf16 v[60:63], v[130:133], v[174:177], 0
	v_mfma_f32_16x16x32_bf16 v[56:59], v[138:141], v[174:177], 0
	v_mfma_f32_16x16x32_bf16 v[44:47], v[130:133], v[182:185], 0
	v_mfma_f32_16x16x32_bf16 v[40:43], v[138:141], v[182:185], 0
	v_mfma_f32_16x16x32_bf16 v[28:31], v[130:133], v[194:197], 0
	v_mfma_f32_16x16x32_bf16 v[24:27], v[138:141], v[194:197], 0
	v_mfma_f32_16x16x32_bf16 v[12:15], v[130:133], v[202:205], 0
	v_mfma_f32_16x16x32_bf16 v[8:11], v[138:141], v[202:205], 0
	v_mfma_f32_16x16x32_bf16 v[60:63], v[134:137], v[178:181], v[60:63]
	v_mfma_f32_16x16x32_bf16 v[56:59], v[142:145], v[178:181], v[56:59]
	v_mfma_f32_16x16x32_bf16 v[44:47], v[134:137], v[190:193], v[44:47]
	v_mfma_f32_16x16x32_bf16 v[40:43], v[142:145], v[190:193], v[40:43]
	v_mfma_f32_16x16x32_bf16 v[28:31], v[134:137], v[198:201], v[28:31]
	v_mfma_f32_16x16x32_bf16 v[24:27], v[142:145], v[198:201], v[24:27]
	v_mfma_f32_16x16x32_bf16 v[12:15], v[134:137], v[206:209], v[12:15]
	v_mfma_f32_16x16x32_bf16 v[8:11], v[142:145], v[206:209], v[8:11]
	v_mfma_f32_16x16x32_bf16 v[52:55], v[146:149], v[174:177], 0
	v_mfma_f32_16x16x32_bf16 v[48:51], v[154:157], v[174:177], 0
	v_mfma_f32_16x16x32_bf16 v[36:39], v[146:149], v[182:185], 0
	v_mfma_f32_16x16x32_bf16 v[32:35], v[154:157], v[182:185], 0
	v_mfma_f32_16x16x32_bf16 v[20:23], v[146:149], v[194:197], 0
	v_mfma_f32_16x16x32_bf16 v[16:19], v[154:157], v[194:197], 0
	v_mfma_f32_16x16x32_bf16 v[4:7], v[146:149], v[202:205], 0
	v_mfma_f32_16x16x32_bf16 v[0:3], v[154:157], v[202:205], 0
	v_mfma_f32_16x16x32_bf16 v[52:55], v[150:153], v[178:181], v[52:55]
	v_mfma_f32_16x16x32_bf16 v[48:51], v[170:173], v[178:181], v[48:51]
	v_mfma_f32_16x16x32_bf16 v[36:39], v[150:153], v[190:193], v[36:39]
	v_mfma_f32_16x16x32_bf16 v[32:35], v[170:173], v[190:193], v[32:35]
	v_mfma_f32_16x16x32_bf16 v[20:23], v[150:153], v[198:201], v[20:23]
	v_mfma_f32_16x16x32_bf16 v[16:19], v[170:173], v[198:201], v[16:19]
	v_mfma_f32_16x16x32_bf16 v[4:7], v[150:153], v[206:209], v[4:7]
	v_mfma_f32_16x16x32_bf16 v[0:3], v[170:173], v[206:209], v[0:3]
	s_setprio 0
	s_barrier
	s_add_i32 s81, 0, 0x18000
	s_add_i32 s84, 0, 0x1c000
	v_add_u32_e32 v142, s81, v186
	v_add_u32_e32 v170, s84, v186
	ds_read_b128 v[130:133], v142
	ds_read_b128 v[134:137], v142 offset:1024
	ds_read_b128 v[138:141], v142 offset:2048
	ds_read_b128 v[142:145], v142 offset:3072
	ds_read_b128 v[146:149], v170
	ds_read_b128 v[150:153], v170 offset:1024
	ds_read_b128 v[154:157], v170 offset:2048
	ds_read_b128 v[170:173], v170 offset:3072
	s_add_u32 s48, s48, s16
	s_addc_u32 s49, s49, 0
	s_mov_b32 m0, s60
	v_lshl_add_u64 v[224:225], s[48:49], 0, v[158:159]
	ds_read_b128 v[174:177], v188 offset:32768
	ds_read_b128 v[178:181], v188 offset:33792
	ds_read_b128 v[182:185], v188 offset:34816
	ds_read_b128 v[190:193], v188 offset:35840
	ds_read_b128 v[194:197], v188 offset:36864
	ds_read_b128 v[198:201], v188 offset:37888
	ds_read_b128 v[202:205], v188 offset:38912
	ds_read_b128 v[206:209], v188 offset:39936
	global_load_lds_dwordx4 v[224:225], off
	v_lshl_add_u64 v[224:225], s[48:49], 0, v[160:161]
	s_mov_b32 m0, s61
	s_nop 0
	global_load_lds_dwordx4 v[224:225], off
	s_waitcnt vmcnt(8)
	s_waitcnt lgkmcnt(0)
	s_barrier
	s_setprio 1
	s_waitcnt lgkmcnt(0)
	v_mfma_f32_16x16x32_bf16 v[126:129], v[130:133], v[174:177], v[126:129]
	v_mfma_f32_16x16x32_bf16 v[122:125], v[138:141], v[174:177], v[122:125]
	v_mfma_f32_16x16x32_bf16 v[110:113], v[130:133], v[182:185], v[110:113]
	v_mfma_f32_16x16x32_bf16 v[106:109], v[138:141], v[182:185], v[106:109]
	v_mfma_f32_16x16x32_bf16 v[92:95], v[130:133], v[194:197], v[92:95]
	v_mfma_f32_16x16x32_bf16 v[88:91], v[138:141], v[194:197], v[88:91]
	v_mfma_f32_16x16x32_bf16 v[76:79], v[130:133], v[202:205], v[76:79]
	v_mfma_f32_16x16x32_bf16 v[72:75], v[138:141], v[202:205], v[72:75]
	v_mfma_f32_16x16x32_bf16 v[126:129], v[134:137], v[178:181], v[126:129]
	v_mfma_f32_16x16x32_bf16 v[122:125], v[142:145], v[178:181], v[122:125]
	v_mfma_f32_16x16x32_bf16 v[110:113], v[134:137], v[190:193], v[110:113]
	v_mfma_f32_16x16x32_bf16 v[106:109], v[142:145], v[190:193], v[106:109]
	v_mfma_f32_16x16x32_bf16 v[92:95], v[134:137], v[198:201], v[92:95]
	v_mfma_f32_16x16x32_bf16 v[88:91], v[142:145], v[198:201], v[88:91]
	v_mfma_f32_16x16x32_bf16 v[76:79], v[134:137], v[206:209], v[76:79]
	v_mfma_f32_16x16x32_bf16 v[72:75], v[142:145], v[206:209], v[72:75]
	v_mfma_f32_16x16x32_bf16 v[118:121], v[146:149], v[174:177], v[118:121]
	v_mfma_f32_16x16x32_bf16 v[114:117], v[154:157], v[174:177], v[114:117]
	v_mfma_f32_16x16x32_bf16 v[102:105], v[146:149], v[182:185], v[102:105]
	v_mfma_f32_16x16x32_bf16 v[98:101], v[154:157], v[182:185], v[98:101]
	v_mfma_f32_16x16x32_bf16 v[84:87], v[146:149], v[194:197], v[84:87]
	v_mfma_f32_16x16x32_bf16 v[80:83], v[154:157], v[194:197], v[80:83]
	v_mfma_f32_16x16x32_bf16 v[68:71], v[146:149], v[202:205], v[68:71]
	v_mfma_f32_16x16x32_bf16 v[64:67], v[154:157], v[202:205], v[64:67]
	v_mfma_f32_16x16x32_bf16 v[118:121], v[150:153], v[178:181], v[118:121]
	v_mfma_f32_16x16x32_bf16 v[114:117], v[170:173], v[178:181], v[114:117]
	v_mfma_f32_16x16x32_bf16 v[102:105], v[150:153], v[190:193], v[102:105]
	v_mfma_f32_16x16x32_bf16 v[98:101], v[170:173], v[190:193], v[98:101]
	v_mfma_f32_16x16x32_bf16 v[84:87], v[150:153], v[198:201], v[84:87]
	v_mfma_f32_16x16x32_bf16 v[80:83], v[170:173], v[198:201], v[80:83]
	v_mfma_f32_16x16x32_bf16 v[68:71], v[150:153], v[206:209], v[68:71]
	v_mfma_f32_16x16x32_bf16 v[64:67], v[170:173], v[206:209], v[64:67]
	s_setprio 0
	s_barrier
	s_add_i32 s48, s81, s8
	v_lshl_add_u64 v[210:211], v[210:211], 0, s[94:95]
	s_mov_b32 m0, s48
	ds_read_b128 v[174:177], v188 offset:49152
	ds_read_b128 v[178:181], v188 offset:50176
	ds_read_b128 v[182:185], v188 offset:51200
	ds_read_b128 v[190:193], v188 offset:52224
	ds_read_b128 v[194:197], v188 offset:53248
	ds_read_b128 v[198:201], v188 offset:54272
	ds_read_b128 v[202:205], v188 offset:55296
	ds_read_b128 v[206:209], v188 offset:56320
	global_load_lds_dwordx4 v[210:211], off
	v_lshl_add_u64 v[210:211], v[212:213], 0, s[94:95]
	s_add_i32 m0, s48, 0x2000
	s_add_i32 s48, s84, s8
	global_load_lds_dwordx4 v[210:211], off
	v_lshl_add_u64 v[210:211], v[216:217], 0, s[94:95]
	s_mov_b32 m0, s48
	s_nop 0
	global_load_lds_dwordx4 v[210:211], off
	v_lshl_add_u64 v[210:211], v[218:219], 0, s[94:95]
	s_add_i32 m0, s48, 0x2000
	s_nop 0
	global_load_lds_dwordx4 v[210:211], off
	v_lshl_add_u64 v[210:211], v[220:221], 0, s[94:95]
	s_mov_b32 m0, s70
	s_nop 0
	global_load_lds_dwordx4 v[210:211], off
	v_lshl_add_u64 v[210:211], v[222:223], 0, s[94:95]
	s_mov_b32 m0, s73
	s_nop 0
	global_load_lds_dwordx4 v[210:211], off
	s_waitcnt vmcnt(8)
	s_waitcnt lgkmcnt(0)
	s_barrier
	s_setprio 1
	s_waitcnt lgkmcnt(0)
	v_mfma_f32_16x16x32_bf16 v[60:63], v[130:133], v[174:177], v[60:63]
	v_mfma_f32_16x16x32_bf16 v[56:59], v[138:141], v[174:177], v[56:59]
	v_mfma_f32_16x16x32_bf16 v[44:47], v[130:133], v[182:185], v[44:47]
	v_mfma_f32_16x16x32_bf16 v[40:43], v[138:141], v[182:185], v[40:43]
	v_mfma_f32_16x16x32_bf16 v[28:31], v[130:133], v[194:197], v[28:31]
	v_mfma_f32_16x16x32_bf16 v[24:27], v[138:141], v[194:197], v[24:27]
	v_mfma_f32_16x16x32_bf16 v[12:15], v[130:133], v[202:205], v[12:15]
	v_mfma_f32_16x16x32_bf16 v[8:11], v[138:141], v[202:205], v[8:11]
	v_mfma_f32_16x16x32_bf16 v[60:63], v[134:137], v[178:181], v[60:63]
	v_mfma_f32_16x16x32_bf16 v[56:59], v[142:145], v[178:181], v[56:59]
	v_mfma_f32_16x16x32_bf16 v[44:47], v[134:137], v[190:193], v[44:47]
	v_mfma_f32_16x16x32_bf16 v[40:43], v[142:145], v[190:193], v[40:43]
	v_mfma_f32_16x16x32_bf16 v[28:31], v[134:137], v[198:201], v[28:31]
	v_mfma_f32_16x16x32_bf16 v[24:27], v[142:145], v[198:201], v[24:27]
	v_mfma_f32_16x16x32_bf16 v[12:15], v[134:137], v[206:209], v[12:15]
	v_mfma_f32_16x16x32_bf16 v[8:11], v[142:145], v[206:209], v[8:11]
	v_mfma_f32_16x16x32_bf16 v[52:55], v[146:149], v[174:177], v[52:55]
	v_mfma_f32_16x16x32_bf16 v[48:51], v[154:157], v[174:177], v[48:51]
	v_mfma_f32_16x16x32_bf16 v[36:39], v[146:149], v[182:185], v[36:39]
	v_mfma_f32_16x16x32_bf16 v[32:35], v[154:157], v[182:185], v[32:35]
	v_mfma_f32_16x16x32_bf16 v[20:23], v[146:149], v[194:197], v[20:23]
	v_mfma_f32_16x16x32_bf16 v[16:19], v[154:157], v[194:197], v[16:19]
	v_mfma_f32_16x16x32_bf16 v[4:7], v[146:149], v[202:205], v[4:7]
	v_mfma_f32_16x16x32_bf16 v[0:3], v[154:157], v[202:205], v[0:3]
	v_mfma_f32_16x16x32_bf16 v[52:55], v[150:153], v[178:181], v[52:55]
	v_mfma_f32_16x16x32_bf16 v[48:51], v[170:173], v[178:181], v[48:51]
	v_mfma_f32_16x16x32_bf16 v[36:39], v[150:153], v[190:193], v[36:39]
	v_mfma_f32_16x16x32_bf16 v[32:35], v[170:173], v[190:193], v[32:35]
	v_mfma_f32_16x16x32_bf16 v[20:23], v[150:153], v[198:201], v[20:23]
	v_mfma_f32_16x16x32_bf16 v[16:19], v[170:173], v[198:201], v[16:19]
	v_mfma_f32_16x16x32_bf16 v[4:7], v[150:153], v[206:209], v[4:7]
	v_mfma_f32_16x16x32_bf16 v[0:3], v[170:173], v[206:209], v[0:3]
	s_setprio 0
	s_barrier
	s_add_u32 s42, s42, 0x100
	s_addc_u32 s43, s43, 0
	s_add_u32 s56, s56, 0x100
	s_addc_u32 s57, s57, 0
	s_cmp_ge_u32 s80, s69
	s_mov_b32 s48, s80
	s_cbranch_scc0 .LBB0_331
	s_branch .Lz331_exit

.LBB0_382:
	s_or_b64 exec, exec, s[42:43]
	s_and_b64 vcc, exec, s[40:41]
	s_mov_b64 s[40:41], -1
	s_cbranch_vccnz .LBB0_319
	s_andn2_b64 vcc, exec, s[20:21]
	s_cbranch_vccnz .LBB0_318
	s_branch .LBB0_318

.LBB0_510:
	s_add_u32 s36, s36, 0x80
	s_addc_u32 s37, s37, 0
	s_add_u32 s48, s48, 0x100
	s_addc_u32 s49, s49, 0
	s_mov_b32 s46, 0
	s_cmp_lt_u32 s69, 2
	s_cbranch_scc1 .Lrb511_skip
	s_andn2_b64 vcc, exec, s[24:25]
	s_cbranch_vccnz .Lrb511_skip
	s_barrier
.Lrb511_skip:
	s_add_i32 s84, s46, 2
	s_add_u32 s86, s36, 0x80
	s_addc_u32 s47, s37, 0
	s_add_i32 vcc_lo, 0, 0x10000
	s_cmp_eq_u32 s33, s46
	s_cselect_b32 s47, s31, s47
	s_cselect_b32 s46, s30, s86
	s_cselect_b32 s87, s35, s49
	s_cselect_b32 s86, s34, s48
	s_add_i32 vcc_hi, 0, 0x14000
	v_add_u32_e32 v154, vcc_lo, v174
	v_add_u32_e32 v172, vcc_hi, v174
	ds_read_b128 v[142:145], v154
	ds_read_b128 v[146:149], v154 offset:1024
	ds_read_b128 v[150:153], v154 offset:2048
	ds_read_b128 v[154:157], v154 offset:3072
	ds_read_b128 v[158:161], v172
	ds_read_b128 v[162:165], v172 offset:1024
	ds_read_b128 v[168:171], v172 offset:2048
	ds_read_b128 v[178:181], v172 offset:3072
	v_lshl_add_u64 v[172:173], s[36:37], 0, v[138:139]
	s_add_i32 m0, s75, 0xc000
	ds_read_b128 v[182:185], v177
	ds_read_b128 v[186:189], v177 offset:1024
	ds_read_b128 v[190:193], v177 offset:2048
	ds_read_b128 v[194:197], v177 offset:3072
	ds_read_b128 v[198:201], v177 offset:4096
	ds_read_b128 v[202:205], v177 offset:5120
	ds_read_b128 v[206:209], v177 offset:6144
	ds_read_b128 v[216:219], v177 offset:7168
	global_load_lds_dwordx4 v[172:173], off
	v_lshl_add_u64 v[172:173], s[36:37], 0, v[140:141]
	s_add_i32 m0, s75, 0xe000
	s_nop 0
	global_load_lds_dwordx4 v[172:173], off
	s_waitcnt vmcnt(8)
	s_waitcnt lgkmcnt(0)
	s_barrier
	s_setprio 1
	s_waitcnt lgkmcnt(0)
	v_mfma_f32_16x16x32_bf16 v[126:129], v[142:145], v[182:185], 0
	v_mfma_f32_16x16x32_bf16 v[122:125], v[150:153], v[182:185], 0
	v_mfma_f32_16x16x32_bf16 v[110:113], v[142:145], v[190:193], 0
	v_mfma_f32_16x16x32_bf16 v[106:109], v[150:153], v[190:193], 0
	v_mfma_f32_16x16x32_bf16 v[92:95], v[142:145], v[198:201], 0
	v_mfma_f32_16x16x32_bf16 v[88:91], v[150:153], v[198:201], 0
	v_mfma_f32_16x16x32_bf16 v[76:79], v[142:145], v[206:209], 0
	v_mfma_f32_16x16x32_bf16 v[72:75], v[150:153], v[206:209], 0
	v_mfma_f32_16x16x32_bf16 v[126:129], v[146:149], v[186:189], v[126:129]
	v_mfma_f32_16x16x32_bf16 v[122:125], v[154:157], v[186:189], v[122:125]
	v_mfma_f32_16x16x32_bf16 v[110:113], v[146:149], v[194:197], v[110:113]
	v_mfma_f32_16x16x32_bf16 v[106:109], v[154:157], v[194:197], v[106:109]
	v_mfma_f32_16x16x32_bf16 v[92:95], v[146:149], v[202:205], v[92:95]
	v_mfma_f32_16x16x32_bf16 v[88:91], v[154:157], v[202:205], v[88:91]
	v_mfma_f32_16x16x32_bf16 v[76:79], v[146:149], v[216:219], v[76:79]
	v_mfma_f32_16x16x32_bf16 v[72:75], v[154:157], v[216:219], v[72:75]
	v_mfma_f32_16x16x32_bf16 v[118:121], v[158:161], v[182:185], 0
	v_mfma_f32_16x16x32_bf16 v[114:117], v[168:171], v[182:185], 0
	v_mfma_f32_16x16x32_bf16 v[102:105], v[158:161], v[190:193], 0
	v_mfma_f32_16x16x32_bf16 v[98:101], v[168:171], v[190:193], 0
	v_mfma_f32_16x16x32_bf16 v[84:87], v[158:161], v[198:201], 0
	v_mfma_f32_16x16x32_bf16 v[80:83], v[168:171], v[198:201], 0
	v_mfma_f32_16x16x32_bf16 v[68:71], v[158:161], v[206:209], 0
	v_mfma_f32_16x16x32_bf16 v[64:67], v[168:171], v[206:209], 0
	v_mfma_f32_16x16x32_bf16 v[118:121], v[162:165], v[186:189], v[118:121]
	v_mfma_f32_16x16x32_bf16 v[114:117], v[178:181], v[186:189], v[114:117]
	v_mfma_f32_16x16x32_bf16 v[102:105], v[162:165], v[194:197], v[102:105]
	v_mfma_f32_16x16x32_bf16 v[98:101], v[178:181], v[194:197], v[98:101]
	v_mfma_f32_16x16x32_bf16 v[84:87], v[162:165], v[202:205], v[84:87]
	v_mfma_f32_16x16x32_bf16 v[80:83], v[178:181], v[202:205], v[80:83]
	v_mfma_f32_16x16x32_bf16 v[68:71], v[162:165], v[216:219], v[68:71]
	v_mfma_f32_16x16x32_bf16 v[64:67], v[178:181], v[216:219], v[64:67]
	s_setprio 0
	s_barrier
	s_add_i32 vcc_lo, vcc_lo, s71
	v_lshl_add_u64 v[172:173], s[86:87], 0, v[96:97]
	s_mov_b32 m0, vcc_lo
	ds_read_b128 v[182:185], v177 offset:16384
	ds_read_b128 v[186:189], v177 offset:17408
	ds_read_b128 v[190:193], v177 offset:18432
	ds_read_b128 v[194:197], v177 offset:19456
	ds_read_b128 v[198:201], v177 offset:20480
	ds_read_b128 v[202:205], v177 offset:21504
	ds_read_b128 v[206:209], v177 offset:22528
	ds_read_b128 v[216:219], v177 offset:23552
	global_load_lds_dwordx4 v[172:173], off
	s_add_i32 m0, vcc_lo, 0x2000
	v_lshl_add_u64 v[210:211], s[86:87], 0, v[134:135]
	s_add_u32 s86, s86, s8
	s_addc_u32 s87, s87, 0
	s_add_i32 vcc_lo, vcc_hi, s71
	global_load_lds_dwordx4 v[210:211], off
	v_lshl_add_u64 v[212:213], s[86:87], 0, v[96:97]
	s_mov_b32 m0, vcc_lo
	v_lshl_add_u64 v[220:221], s[86:87], 0, v[134:135]
	global_load_lds_dwordx4 v[212:213], off
	s_add_i32 m0, vcc_lo, 0x2000
	v_lshl_add_u64 v[222:223], s[46:47], 0, v[130:131]
	global_load_lds_dwordx4 v[220:221], off
	s_mov_b32 m0, s75
	v_lshl_add_u64 v[224:225], s[46:47], 0, v[132:133]
	global_load_lds_dwordx4 v[222:223], off
	s_mov_b32 m0, s76
	s_nop 0
	global_load_lds_dwordx4 v[224:225], off
	s_waitcnt vmcnt(8)
	s_waitcnt lgkmcnt(0)
	s_barrier
	s_setprio 1
	s_waitcnt lgkmcnt(0)
	v_mfma_f32_16x16x32_bf16 v[60:63], v[142:145], v[182:185], 0
	v_mfma_f32_16x16x32_bf16 v[56:59], v[150:153], v[182:185], 0
	v_mfma_f32_16x16x32_bf16 v[44:47], v[142:145], v[190:193], 0
	v_mfma_f32_16x16x32_bf16 v[40:43], v[150:153], v[190:193], 0
	v_mfma_f32_16x16x32_bf16 v[28:31], v[142:145], v[198:201], 0
	v_mfma_f32_16x16x32_bf16 v[24:27], v[150:153], v[198:201], 0
	v_mfma_f32_16x16x32_bf16 v[12:15], v[142:145], v[206:209], 0
	v_mfma_f32_16x16x32_bf16 v[8:11], v[150:153], v[206:209], 0
	v_mfma_f32_16x16x32_bf16 v[60:63], v[146:149], v[186:189], v[60:63]
	v_mfma_f32_16x16x32_bf16 v[56:59], v[154:157], v[186:189], v[56:59]
	v_mfma_f32_16x16x32_bf16 v[44:47], v[146:149], v[194:197], v[44:47]
	v_mfma_f32_16x16x32_bf16 v[40:43], v[154:157], v[194:197], v[40:43]
	v_mfma_f32_16x16x32_bf16 v[28:31], v[146:149], v[202:205], v[28:31]
	v_mfma_f32_16x16x32_bf16 v[24:27], v[154:157], v[202:205], v[24:27]
	v_mfma_f32_16x16x32_bf16 v[12:15], v[146:149], v[216:219], v[12:15]
	v_mfma_f32_16x16x32_bf16 v[8:11], v[154:157], v[216:219], v[8:11]
	v_mfma_f32_16x16x32_bf16 v[52:55], v[158:161], v[182:185], 0
	v_mfma_f32_16x16x32_bf16 v[48:51], v[168:171], v[182:185], 0
	v_mfma_f32_16x16x32_bf16 v[36:39], v[158:161], v[190:193], 0
	v_mfma_f32_16x16x32_bf16 v[32:35], v[168:171], v[190:193], 0
	v_mfma_f32_16x16x32_bf16 v[20:23], v[158:161], v[198:201], 0
	v_mfma_f32_16x16x32_bf16 v[16:19], v[168:171], v[198:201], 0
	v_mfma_f32_16x16x32_bf16 v[4:7], v[158:161], v[206:209], 0
	v_mfma_f32_16x16x32_bf16 v[0:3], v[168:171], v[206:209], 0
	v_mfma_f32_16x16x32_bf16 v[52:55], v[162:165], v[186:189], v[52:55]
	v_mfma_f32_16x16x32_bf16 v[48:51], v[178:181], v[186:189], v[48:51]
	v_mfma_f32_16x16x32_bf16 v[36:39], v[162:165], v[194:197], v[36:39]
	v_mfma_f32_16x16x32_bf16 v[32:35], v[178:181], v[194:197], v[32:35]
	v_mfma_f32_16x16x32_bf16 v[20:23], v[162:165], v[202:205], v[20:23]
	v_mfma_f32_16x16x32_bf16 v[16:19], v[178:181], v[202:205], v[16:19]
	v_mfma_f32_16x16x32_bf16 v[4:7], v[162:165], v[216:219], v[4:7]
	v_mfma_f32_16x16x32_bf16 v[0:3], v[178:181], v[216:219], v[0:3]
	s_setprio 0
	s_barrier
	s_add_i32 s86, 0, 0x18000
	s_add_i32 s87, 0, 0x1c000
	v_add_u32_e32 v154, s86, v174
	v_add_u32_e32 v178, s87, v174
	ds_read_b128 v[142:145], v154
	ds_read_b128 v[146:149], v154 offset:1024
	ds_read_b128 v[150:153], v154 offset:2048
	ds_read_b128 v[154:157], v154 offset:3072
	ds_read_b128 v[158:161], v178
	ds_read_b128 v[162:165], v178 offset:1024
	ds_read_b128 v[168:171], v178 offset:2048
	ds_read_b128 v[178:181], v178 offset:3072
	s_add_u32 s46, s46, s20
	s_addc_u32 s47, s47, 0
	s_mov_b32 m0, s77
	v_lshl_add_u64 v[226:227], s[46:47], 0, v[130:131]
	ds_read_b128 v[182:185], v177 offset:32768
	ds_read_b128 v[186:189], v177 offset:33792
	ds_read_b128 v[190:193], v177 offset:34816
	ds_read_b128 v[194:197], v177 offset:35840
	ds_read_b128 v[198:201], v177 offset:36864
	ds_read_b128 v[202:205], v177 offset:37888
	ds_read_b128 v[206:209], v177 offset:38912
	ds_read_b128 v[216:219], v177 offset:39936
	global_load_lds_dwordx4 v[226:227], off
	v_lshl_add_u64 v[226:227], s[46:47], 0, v[132:133]
	s_mov_b32 m0, s78
	s_nop 0
	global_load_lds_dwordx4 v[226:227], off
	s_waitcnt vmcnt(8)
	s_waitcnt lgkmcnt(0)
	s_barrier
	s_setprio 1
	s_waitcnt lgkmcnt(0)
	v_mfma_f32_16x16x32_bf16 v[126:129], v[142:145], v[182:185], v[126:129]
	v_mfma_f32_16x16x32_bf16 v[122:125], v[150:153], v[182:185], v[122:125]
	v_mfma_f32_16x16x32_bf16 v[110:113], v[142:145], v[190:193], v[110:113]
	v_mfma_f32_16x16x32_bf16 v[106:109], v[150:153], v[190:193], v[106:109]
	v_mfma_f32_16x16x32_bf16 v[92:95], v[142:145], v[198:201], v[92:95]
	v_mfma_f32_16x16x32_bf16 v[88:91], v[150:153], v[198:201], v[88:91]
	v_mfma_f32_16x16x32_bf16 v[76:79], v[142:145], v[206:209], v[76:79]
	v_mfma_f32_16x16x32_bf16 v[72:75], v[150:153], v[206:209], v[72:75]
	v_mfma_f32_16x16x32_bf16 v[126:129], v[146:149], v[186:189], v[126:129]
	v_mfma_f32_16x16x32_bf16 v[122:125], v[154:157], v[186:189], v[122:125]
	v_mfma_f32_16x16x32_bf16 v[110:113], v[146:149], v[194:197], v[110:113]
	v_mfma_f32_16x16x32_bf16 v[106:109], v[154:157], v[194:197], v[106:109]
	v_mfma_f32_16x16x32_bf16 v[92:95], v[146:149], v[202:205], v[92:95]
	v_mfma_f32_16x16x32_bf16 v[88:91], v[154:157], v[202:205], v[88:91]
	v_mfma_f32_16x16x32_bf16 v[76:79], v[146:149], v[216:219], v[76:79]
	v_mfma_f32_16x16x32_bf16 v[72:75], v[154:157], v[216:219], v[72:75]
	v_mfma_f32_16x16x32_bf16 v[118:121], v[158:161], v[182:185], v[118:121]
	v_mfma_f32_16x16x32_bf16 v[114:117], v[168:171], v[182:185], v[114:117]
	v_mfma_f32_16x16x32_bf16 v[102:105], v[158:161], v[190:193], v[102:105]
	v_mfma_f32_16x16x32_bf16 v[98:101], v[168:171], v[190:193], v[98:101]
	v_mfma_f32_16x16x32_bf16 v[84:87], v[158:161], v[198:201], v[84:87]
	v_mfma_f32_16x16x32_bf16 v[80:83], v[168:171], v[198:201], v[80:83]
	v_mfma_f32_16x16x32_bf16 v[68:71], v[158:161], v[206:209], v[68:71]
	v_mfma_f32_16x16x32_bf16 v[64:67], v[168:171], v[206:209], v[64:67]
	v_mfma_f32_16x16x32_bf16 v[118:121], v[162:165], v[186:189], v[118:121]
	v_mfma_f32_16x16x32_bf16 v[114:117], v[178:181], v[186:189], v[114:117]
	v_mfma_f32_16x16x32_bf16 v[102:105], v[162:165], v[194:197], v[102:105]
	v_mfma_f32_16x16x32_bf16 v[98:101], v[178:181], v[194:197], v[98:101]
	v_mfma_f32_16x16x32_bf16 v[84:87], v[162:165], v[202:205], v[84:87]
	v_mfma_f32_16x16x32_bf16 v[80:83], v[178:181], v[202:205], v[80:83]
	v_mfma_f32_16x16x32_bf16 v[68:71], v[162:165], v[216:219], v[68:71]
	v_mfma_f32_16x16x32_bf16 v[64:67], v[178:181], v[216:219], v[64:67]
	s_setprio 0
	s_barrier
	s_add_i32 s46, s86, s71
	v_lshl_add_u64 v[172:173], v[172:173], 0, s[94:95]
	s_mov_b32 m0, s46
	ds_read_b128 v[182:185], v177 offset:49152
	ds_read_b128 v[186:189], v177 offset:50176
	ds_read_b128 v[190:193], v177 offset:51200
	ds_read_b128 v[194:197], v177 offset:52224
	ds_read_b128 v[198:201], v177 offset:53248
	ds_read_b128 v[202:205], v177 offset:54272
	ds_read_b128 v[206:209], v177 offset:55296
	ds_read_b128 v[216:219], v177 offset:56320
	global_load_lds_dwordx4 v[172:173], off
	v_lshl_add_u64 v[172:173], v[210:211], 0, s[94:95]
	s_add_i32 m0, s46, 0x2000
	s_add_i32 s46, s87, s71
	global_load_lds_dwordx4 v[172:173], off
	v_lshl_add_u64 v[172:173], v[212:213], 0, s[94:95]
	s_mov_b32 m0, s46
	s_nop 0
	global_load_lds_dwordx4 v[172:173], off
	v_lshl_add_u64 v[172:173], v[220:221], 0, s[94:95]
	s_add_i32 m0, s46, 0x2000
	s_nop 0
	global_load_lds_dwordx4 v[172:173], off
	v_lshl_add_u64 v[172:173], v[222:223], 0, s[94:95]
	s_mov_b32 m0, s79
	s_nop 0
	global_load_lds_dwordx4 v[172:173], off
	v_lshl_add_u64 v[172:173], v[224:225], 0, s[94:95]
	s_mov_b32 m0, s80
	s_nop 0
	global_load_lds_dwordx4 v[172:173], off
	s_waitcnt vmcnt(8)
	s_waitcnt lgkmcnt(0)
	s_barrier
	s_setprio 1
	s_waitcnt lgkmcnt(0)
	v_mfma_f32_16x16x32_bf16 v[60:63], v[142:145], v[182:185], v[60:63]
	v_mfma_f32_16x16x32_bf16 v[56:59], v[150:153], v[182:185], v[56:59]
	v_mfma_f32_16x16x32_bf16 v[44:47], v[142:145], v[190:193], v[44:47]
	v_mfma_f32_16x16x32_bf16 v[40:43], v[150:153], v[190:193], v[40:43]
	v_mfma_f32_16x16x32_bf16 v[28:31], v[142:145], v[198:201], v[28:31]
	v_mfma_f32_16x16x32_bf16 v[24:27], v[150:153], v[198:201], v[24:27]
	v_mfma_f32_16x16x32_bf16 v[12:15], v[142:145], v[206:209], v[12:15]
	v_mfma_f32_16x16x32_bf16 v[8:11], v[150:153], v[206:209], v[8:11]
	v_mfma_f32_16x16x32_bf16 v[60:63], v[146:149], v[186:189], v[60:63]
	v_mfma_f32_16x16x32_bf16 v[56:59], v[154:157], v[186:189], v[56:59]
	v_mfma_f32_16x16x32_bf16 v[44:47], v[146:149], v[194:197], v[44:47]
	v_mfma_f32_16x16x32_bf16 v[40:43], v[154:157], v[194:197], v[40:43]
	v_mfma_f32_16x16x32_bf16 v[28:31], v[146:149], v[202:205], v[28:31]
	v_mfma_f32_16x16x32_bf16 v[24:27], v[154:157], v[202:205], v[24:27]
	v_mfma_f32_16x16x32_bf16 v[12:15], v[146:149], v[216:219], v[12:15]
	v_mfma_f32_16x16x32_bf16 v[8:11], v[154:157], v[216:219], v[8:11]
	v_mfma_f32_16x16x32_bf16 v[52:55], v[158:161], v[182:185], v[52:55]
	v_mfma_f32_16x16x32_bf16 v[48:51], v[168:171], v[182:185], v[48:51]
	v_mfma_f32_16x16x32_bf16 v[36:39], v[158:161], v[190:193], v[36:39]
	v_mfma_f32_16x16x32_bf16 v[32:35], v[168:171], v[190:193], v[32:35]
	v_mfma_f32_16x16x32_bf16 v[20:23], v[158:161], v[198:201], v[20:23]
	v_mfma_f32_16x16x32_bf16 v[16:19], v[168:171], v[198:201], v[16:19]
	v_mfma_f32_16x16x32_bf16 v[4:7], v[158:161], v[206:209], v[4:7]
	v_mfma_f32_16x16x32_bf16 v[0:3], v[168:171], v[206:209], v[0:3]
	v_mfma_f32_16x16x32_bf16 v[52:55], v[162:165], v[186:189], v[52:55]
	v_mfma_f32_16x16x32_bf16 v[48:51], v[178:181], v[186:189], v[48:51]
	v_mfma_f32_16x16x32_bf16 v[36:39], v[162:165], v[194:197], v[36:39]
	v_mfma_f32_16x16x32_bf16 v[32:35], v[178:181], v[194:197], v[32:35]
	v_mfma_f32_16x16x32_bf16 v[20:23], v[162:165], v[202:205], v[20:23]
	v_mfma_f32_16x16x32_bf16 v[16:19], v[178:181], v[202:205], v[16:19]
	v_mfma_f32_16x16x32_bf16 v[4:7], v[162:165], v[216:219], v[4:7]
	v_mfma_f32_16x16x32_bf16 v[0:3], v[178:181], v[216:219], v[0:3]
	s_setprio 0
	s_barrier
	s_add_u32 s36, s36, 0x100
	s_addc_u32 s37, s37, 0
	s_add_u32 s48, s48, 0x100
	s_addc_u32 s49, s49, 0
	s_cmp_ge_u32 s84, s2
	s_mov_b32 s46, s84
	s_cbranch_scc0 .LBB0_511
	s_branch .Lz511_exit

.LBB0_634:
	s_andn2_b64 vcc, exec, s[24:25]
	s_cbranch_vccnz .LBB0_502
	s_branch .LBB0_502

.LBB0_653:
	s_add_u32 s34, s34, 0x80
	s_addc_u32 s35, s35, 0
	s_add_u32 s46, s36, 0x100
	s_addc_u32 s47, s37, 0
	s_mov_b32 s36, 0
	s_cmp_lt_u32 s69, 2
	s_cbranch_scc1 .Lrb654_skip
	s_andn2_b64 vcc, exec, s[24:25]
	s_cbranch_vccnz .Lrb654_skip
	s_barrier
.Lrb654_skip:
	s_add_i32 s56, s36, 2
	s_add_u32 s57, s34, 0x80
	s_addc_u32 s37, s35, 0
	s_add_i32 s84, 0, 0x10000
	s_cmp_eq_u32 s2, s36
	s_cselect_b32 s37, s9, s37
	s_cselect_b32 s36, s8, s57
	s_cselect_b32 vcc_hi, s31, s47
	s_cselect_b32 vcc_lo, s30, s46
	s_add_i32 s57, 0, 0x14000
	v_add_u32_e32 v154, s84, v174
	v_add_u32_e32 v172, s57, v174
	ds_read_b128 v[142:145], v154
	ds_read_b128 v[146:149], v154 offset:1024
	ds_read_b128 v[150:153], v154 offset:2048
	ds_read_b128 v[154:157], v154 offset:3072
	ds_read_b128 v[158:161], v172
	ds_read_b128 v[162:165], v172 offset:1024
	ds_read_b128 v[168:171], v172 offset:2048
	ds_read_b128 v[178:181], v172 offset:3072
	v_lshl_add_u64 v[172:173], s[34:35], 0, v[138:139]
	s_add_i32 m0, s77, 0xc000
	ds_read_b128 v[182:185], v177
	ds_read_b128 v[186:189], v177 offset:1024
	ds_read_b128 v[190:193], v177 offset:2048
	ds_read_b128 v[194:197], v177 offset:3072
	ds_read_b128 v[198:201], v177 offset:4096
	ds_read_b128 v[202:205], v177 offset:5120
	ds_read_b128 v[206:209], v177 offset:6144
	ds_read_b128 v[216:219], v177 offset:7168
	global_load_lds_dwordx4 v[172:173], off
	v_lshl_add_u64 v[172:173], s[34:35], 0, v[140:141]
	s_add_i32 m0, s77, 0xe000
	s_nop 0
	global_load_lds_dwordx4 v[172:173], off
	s_waitcnt vmcnt(8)
	s_waitcnt lgkmcnt(0)
	s_barrier
	s_setprio 1
	s_waitcnt lgkmcnt(0)
	v_mfma_f32_16x16x32_f16 v[126:129], v[142:145], v[182:185], 0
	v_mfma_f32_16x16x32_f16 v[122:125], v[150:153], v[182:185], 0
	v_mfma_f32_16x16x32_f16 v[110:113], v[142:145], v[190:193], 0
	v_mfma_f32_16x16x32_f16 v[106:109], v[150:153], v[190:193], 0
	v_mfma_f32_16x16x32_f16 v[92:95], v[142:145], v[198:201], 0
	v_mfma_f32_16x16x32_f16 v[88:91], v[150:153], v[198:201], 0
	v_mfma_f32_16x16x32_f16 v[76:79], v[142:145], v[206:209], 0
	v_mfma_f32_16x16x32_f16 v[72:75], v[150:153], v[206:209], 0
	v_mfma_f32_16x16x32_f16 v[126:129], v[146:149], v[186:189], v[126:129]
	v_mfma_f32_16x16x32_f16 v[122:125], v[154:157], v[186:189], v[122:125]
	v_mfma_f32_16x16x32_f16 v[110:113], v[146:149], v[194:197], v[110:113]
	v_mfma_f32_16x16x32_f16 v[106:109], v[154:157], v[194:197], v[106:109]
	v_mfma_f32_16x16x32_f16 v[92:95], v[146:149], v[202:205], v[92:95]
	v_mfma_f32_16x16x32_f16 v[88:91], v[154:157], v[202:205], v[88:91]
	v_mfma_f32_16x16x32_f16 v[76:79], v[146:149], v[216:219], v[76:79]
	v_mfma_f32_16x16x32_f16 v[72:75], v[154:157], v[216:219], v[72:75]
	v_mfma_f32_16x16x32_f16 v[118:121], v[158:161], v[182:185], 0
	v_mfma_f32_16x16x32_f16 v[114:117], v[168:171], v[182:185], 0
	v_mfma_f32_16x16x32_f16 v[102:105], v[158:161], v[190:193], 0
	v_mfma_f32_16x16x32_f16 v[98:101], v[168:171], v[190:193], 0
	v_mfma_f32_16x16x32_f16 v[84:87], v[158:161], v[198:201], 0
	v_mfma_f32_16x16x32_f16 v[80:83], v[168:171], v[198:201], 0
	v_mfma_f32_16x16x32_f16 v[68:71], v[158:161], v[206:209], 0
	v_mfma_f32_16x16x32_f16 v[64:67], v[168:171], v[206:209], 0
	v_mfma_f32_16x16x32_f16 v[118:121], v[162:165], v[186:189], v[118:121]
	v_mfma_f32_16x16x32_f16 v[114:117], v[178:181], v[186:189], v[114:117]
	v_mfma_f32_16x16x32_f16 v[102:105], v[162:165], v[194:197], v[102:105]
	v_mfma_f32_16x16x32_f16 v[98:101], v[178:181], v[194:197], v[98:101]
	v_mfma_f32_16x16x32_f16 v[84:87], v[162:165], v[202:205], v[84:87]
	v_mfma_f32_16x16x32_f16 v[80:83], v[178:181], v[202:205], v[80:83]
	v_mfma_f32_16x16x32_f16 v[68:71], v[162:165], v[216:219], v[68:71]
	v_mfma_f32_16x16x32_f16 v[64:67], v[178:181], v[216:219], v[64:67]
	s_setprio 0
	s_barrier
	s_add_i32 s84, s84, s76
	v_lshl_add_u64 v[172:173], vcc, 0, v[96:97]
	s_mov_b32 m0, s84
	ds_read_b128 v[182:185], v177 offset:16384
	ds_read_b128 v[186:189], v177 offset:17408
	ds_read_b128 v[190:193], v177 offset:18432
	ds_read_b128 v[194:197], v177 offset:19456
	ds_read_b128 v[198:201], v177 offset:20480
	ds_read_b128 v[202:205], v177 offset:21504
	ds_read_b128 v[206:209], v177 offset:22528
	ds_read_b128 v[216:219], v177 offset:23552
	global_load_lds_dwordx4 v[172:173], off
	s_add_i32 m0, s84, 0x2000
	v_lshl_add_u64 v[210:211], vcc, 0, v[134:135]
	s_add_u32 vcc_lo, vcc_lo, s71
	s_addc_u32 vcc_hi, vcc_hi, 0
	s_add_i32 s57, s57, s76
	global_load_lds_dwordx4 v[210:211], off
	v_lshl_add_u64 v[212:213], vcc, 0, v[96:97]
	s_mov_b32 m0, s57
	v_lshl_add_u64 v[220:221], vcc, 0, v[134:135]
	global_load_lds_dwordx4 v[212:213], off
	s_add_i32 m0, s57, 0x2000
	v_lshl_add_u64 v[222:223], s[36:37], 0, v[130:131]
	global_load_lds_dwordx4 v[220:221], off
	s_mov_b32 m0, s77
	v_lshl_add_u64 v[224:225], s[36:37], 0, v[132:133]
	global_load_lds_dwordx4 v[222:223], off
	s_mov_b32 m0, s78
	s_nop 0
	global_load_lds_dwordx4 v[224:225], off
	s_waitcnt vmcnt(8)
	s_waitcnt lgkmcnt(0)
	s_barrier
	s_setprio 1
	s_waitcnt lgkmcnt(0)
	v_mfma_f32_16x16x32_f16 v[60:63], v[142:145], v[182:185], 0
	v_mfma_f32_16x16x32_f16 v[56:59], v[150:153], v[182:185], 0
	v_mfma_f32_16x16x32_f16 v[44:47], v[142:145], v[190:193], 0
	v_mfma_f32_16x16x32_f16 v[40:43], v[150:153], v[190:193], 0
	v_mfma_f32_16x16x32_f16 v[28:31], v[142:145], v[198:201], 0
	v_mfma_f32_16x16x32_f16 v[24:27], v[150:153], v[198:201], 0
	v_mfma_f32_16x16x32_f16 v[12:15], v[142:145], v[206:209], 0
	v_mfma_f32_16x16x32_f16 v[8:11], v[150:153], v[206:209], 0
	v_mfma_f32_16x16x32_f16 v[60:63], v[146:149], v[186:189], v[60:63]
	v_mfma_f32_16x16x32_f16 v[56:59], v[154:157], v[186:189], v[56:59]
	v_mfma_f32_16x16x32_f16 v[44:47], v[146:149], v[194:197], v[44:47]
	v_mfma_f32_16x16x32_f16 v[40:43], v[154:157], v[194:197], v[40:43]
	v_mfma_f32_16x16x32_f16 v[28:31], v[146:149], v[202:205], v[28:31]
	v_mfma_f32_16x16x32_f16 v[24:27], v[154:157], v[202:205], v[24:27]
	v_mfma_f32_16x16x32_f16 v[12:15], v[146:149], v[216:219], v[12:15]
	v_mfma_f32_16x16x32_f16 v[8:11], v[154:157], v[216:219], v[8:11]
	v_mfma_f32_16x16x32_f16 v[52:55], v[158:161], v[182:185], 0
	v_mfma_f32_16x16x32_f16 v[48:51], v[168:171], v[182:185], 0
	v_mfma_f32_16x16x32_f16 v[36:39], v[158:161], v[190:193], 0
	v_mfma_f32_16x16x32_f16 v[32:35], v[168:171], v[190:193], 0
	v_mfma_f32_16x16x32_f16 v[20:23], v[158:161], v[198:201], 0
	v_mfma_f32_16x16x32_f16 v[16:19], v[168:171], v[198:201], 0
	v_mfma_f32_16x16x32_f16 v[4:7], v[158:161], v[206:209], 0
	v_mfma_f32_16x16x32_f16 v[0:3], v[168:171], v[206:209], 0
	v_mfma_f32_16x16x32_f16 v[52:55], v[162:165], v[186:189], v[52:55]
	v_mfma_f32_16x16x32_f16 v[48:51], v[178:181], v[186:189], v[48:51]
	v_mfma_f32_16x16x32_f16 v[36:39], v[162:165], v[194:197], v[36:39]
	v_mfma_f32_16x16x32_f16 v[32:35], v[178:181], v[194:197], v[32:35]
	v_mfma_f32_16x16x32_f16 v[20:23], v[162:165], v[202:205], v[20:23]
	v_mfma_f32_16x16x32_f16 v[16:19], v[178:181], v[202:205], v[16:19]
	v_mfma_f32_16x16x32_f16 v[4:7], v[162:165], v[216:219], v[4:7]
	v_mfma_f32_16x16x32_f16 v[0:3], v[178:181], v[216:219], v[0:3]
	s_setprio 0
	s_barrier
	s_add_i32 s57, 0, 0x18000
	s_add_i32 s84, 0, 0x1c000
	v_add_u32_e32 v154, s57, v174
	v_add_u32_e32 v178, s84, v174
	ds_read_b128 v[142:145], v154
	ds_read_b128 v[146:149], v154 offset:1024
	ds_read_b128 v[150:153], v154 offset:2048
	ds_read_b128 v[154:157], v154 offset:3072
	ds_read_b128 v[158:161], v178
	ds_read_b128 v[162:165], v178 offset:1024
	ds_read_b128 v[168:171], v178 offset:2048
	ds_read_b128 v[178:181], v178 offset:3072
	s_add_u32 s36, s36, s20
	s_addc_u32 s37, s37, 0
	s_mov_b32 m0, s79
	v_lshl_add_u64 v[226:227], s[36:37], 0, v[130:131]
	ds_read_b128 v[182:185], v177 offset:32768
	ds_read_b128 v[186:189], v177 offset:33792
	ds_read_b128 v[190:193], v177 offset:34816
	ds_read_b128 v[194:197], v177 offset:35840
	ds_read_b128 v[198:201], v177 offset:36864
	ds_read_b128 v[202:205], v177 offset:37888
	ds_read_b128 v[206:209], v177 offset:38912
	ds_read_b128 v[216:219], v177 offset:39936
	global_load_lds_dwordx4 v[226:227], off
	v_lshl_add_u64 v[226:227], s[36:37], 0, v[132:133]
	s_mov_b32 m0, s80
	s_nop 0
	global_load_lds_dwordx4 v[226:227], off
	s_waitcnt vmcnt(8)
	s_waitcnt lgkmcnt(0)
	s_barrier
	s_setprio 1
	s_waitcnt lgkmcnt(0)
	v_mfma_f32_16x16x32_f16 v[126:129], v[142:145], v[182:185], v[126:129]
	v_mfma_f32_16x16x32_f16 v[122:125], v[150:153], v[182:185], v[122:125]
	v_mfma_f32_16x16x32_f16 v[110:113], v[142:145], v[190:193], v[110:113]
	v_mfma_f32_16x16x32_f16 v[106:109], v[150:153], v[190:193], v[106:109]
	v_mfma_f32_16x16x32_f16 v[92:95], v[142:145], v[198:201], v[92:95]
	v_mfma_f32_16x16x32_f16 v[88:91], v[150:153], v[198:201], v[88:91]
	v_mfma_f32_16x16x32_f16 v[76:79], v[142:145], v[206:209], v[76:79]
	v_mfma_f32_16x16x32_f16 v[72:75], v[150:153], v[206:209], v[72:75]
	v_mfma_f32_16x16x32_f16 v[126:129], v[146:149], v[186:189], v[126:129]
	v_mfma_f32_16x16x32_f16 v[122:125], v[154:157], v[186:189], v[122:125]
	v_mfma_f32_16x16x32_f16 v[110:113], v[146:149], v[194:197], v[110:113]
	v_mfma_f32_16x16x32_f16 v[106:109], v[154:157], v[194:197], v[106:109]
	v_mfma_f32_16x16x32_f16 v[92:95], v[146:149], v[202:205], v[92:95]
	v_mfma_f32_16x16x32_f16 v[88:91], v[154:157], v[202:205], v[88:91]
	v_mfma_f32_16x16x32_f16 v[76:79], v[146:149], v[216:219], v[76:79]
	v_mfma_f32_16x16x32_f16 v[72:75], v[154:157], v[216:219], v[72:75]
	v_mfma_f32_16x16x32_f16 v[118:121], v[158:161], v[182:185], v[118:121]
	v_mfma_f32_16x16x32_f16 v[114:117], v[168:171], v[182:185], v[114:117]
	v_mfma_f32_16x16x32_f16 v[102:105], v[158:161], v[190:193], v[102:105]
	v_mfma_f32_16x16x32_f16 v[98:101], v[168:171], v[190:193], v[98:101]
	v_mfma_f32_16x16x32_f16 v[84:87], v[158:161], v[198:201], v[84:87]
	v_mfma_f32_16x16x32_f16 v[80:83], v[168:171], v[198:201], v[80:83]
	v_mfma_f32_16x16x32_f16 v[68:71], v[158:161], v[206:209], v[68:71]
	v_mfma_f32_16x16x32_f16 v[64:67], v[168:171], v[206:209], v[64:67]
	v_mfma_f32_16x16x32_f16 v[118:121], v[162:165], v[186:189], v[118:121]
	v_mfma_f32_16x16x32_f16 v[114:117], v[178:181], v[186:189], v[114:117]
	v_mfma_f32_16x16x32_f16 v[102:105], v[162:165], v[194:197], v[102:105]
	v_mfma_f32_16x16x32_f16 v[98:101], v[178:181], v[194:197], v[98:101]
	v_mfma_f32_16x16x32_f16 v[84:87], v[162:165], v[202:205], v[84:87]
	v_mfma_f32_16x16x32_f16 v[80:83], v[178:181], v[202:205], v[80:83]
	v_mfma_f32_16x16x32_f16 v[68:71], v[162:165], v[216:219], v[68:71]
	v_mfma_f32_16x16x32_f16 v[64:67], v[178:181], v[216:219], v[64:67]
	s_setprio 0
	s_barrier
	s_add_i32 s36, s57, s76
	v_lshl_add_u64 v[172:173], v[172:173], 0, s[94:95]
	s_mov_b32 m0, s36
	ds_read_b128 v[182:185], v177 offset:49152
	ds_read_b128 v[186:189], v177 offset:50176
	ds_read_b128 v[190:193], v177 offset:51200
	ds_read_b128 v[194:197], v177 offset:52224
	ds_read_b128 v[198:201], v177 offset:53248
	ds_read_b128 v[202:205], v177 offset:54272
	ds_read_b128 v[206:209], v177 offset:55296
	ds_read_b128 v[216:219], v177 offset:56320
	global_load_lds_dwordx4 v[172:173], off
	v_lshl_add_u64 v[172:173], v[210:211], 0, s[94:95]
	s_add_i32 m0, s36, 0x2000
	s_add_i32 s36, s84, s76
	global_load_lds_dwordx4 v[172:173], off
	v_lshl_add_u64 v[172:173], v[212:213], 0, s[94:95]
	s_mov_b32 m0, s36
	s_nop 0
	global_load_lds_dwordx4 v[172:173], off
	v_lshl_add_u64 v[172:173], v[220:221], 0, s[94:95]
	s_add_i32 m0, s36, 0x2000
	s_nop 0
	global_load_lds_dwordx4 v[172:173], off
	v_lshl_add_u64 v[172:173], v[222:223], 0, s[94:95]
	s_mov_b32 m0, s81
	s_nop 0
	global_load_lds_dwordx4 v[172:173], off
	v_lshl_add_u64 v[172:173], v[224:225], 0, s[94:95]
	s_mov_b32 m0, s99
	s_nop 0
	global_load_lds_dwordx4 v[172:173], off
	s_waitcnt vmcnt(8)
	s_waitcnt lgkmcnt(0)
	s_barrier
	s_setprio 1
	s_waitcnt lgkmcnt(0)
	v_mfma_f32_16x16x32_f16 v[60:63], v[142:145], v[182:185], v[60:63]
	v_mfma_f32_16x16x32_f16 v[56:59], v[150:153], v[182:185], v[56:59]
	v_mfma_f32_16x16x32_f16 v[44:47], v[142:145], v[190:193], v[44:47]
	v_mfma_f32_16x16x32_f16 v[40:43], v[150:153], v[190:193], v[40:43]
	v_mfma_f32_16x16x32_f16 v[28:31], v[142:145], v[198:201], v[28:31]
	v_mfma_f32_16x16x32_f16 v[24:27], v[150:153], v[198:201], v[24:27]
	v_mfma_f32_16x16x32_f16 v[12:15], v[142:145], v[206:209], v[12:15]
	v_mfma_f32_16x16x32_f16 v[8:11], v[150:153], v[206:209], v[8:11]
	v_mfma_f32_16x16x32_f16 v[60:63], v[146:149], v[186:189], v[60:63]
	v_mfma_f32_16x16x32_f16 v[56:59], v[154:157], v[186:189], v[56:59]
	v_mfma_f32_16x16x32_f16 v[44:47], v[146:149], v[194:197], v[44:47]
	v_mfma_f32_16x16x32_f16 v[40:43], v[154:157], v[194:197], v[40:43]
	v_mfma_f32_16x16x32_f16 v[28:31], v[146:149], v[202:205], v[28:31]
	v_mfma_f32_16x16x32_f16 v[24:27], v[154:157], v[202:205], v[24:27]
	v_mfma_f32_16x16x32_f16 v[12:15], v[146:149], v[216:219], v[12:15]
	v_mfma_f32_16x16x32_f16 v[8:11], v[154:157], v[216:219], v[8:11]
	v_mfma_f32_16x16x32_f16 v[52:55], v[158:161], v[182:185], v[52:55]
	v_mfma_f32_16x16x32_f16 v[48:51], v[168:171], v[182:185], v[48:51]
	v_mfma_f32_16x16x32_f16 v[36:39], v[158:161], v[190:193], v[36:39]
	v_mfma_f32_16x16x32_f16 v[32:35], v[168:171], v[190:193], v[32:35]
	v_mfma_f32_16x16x32_f16 v[20:23], v[158:161], v[198:201], v[20:23]
	v_mfma_f32_16x16x32_f16 v[16:19], v[168:171], v[198:201], v[16:19]
	v_mfma_f32_16x16x32_f16 v[4:7], v[158:161], v[206:209], v[4:7]
	v_mfma_f32_16x16x32_f16 v[0:3], v[168:171], v[206:209], v[0:3]
	v_mfma_f32_16x16x32_f16 v[52:55], v[162:165], v[186:189], v[52:55]
	v_mfma_f32_16x16x32_f16 v[48:51], v[178:181], v[186:189], v[48:51]
	v_mfma_f32_16x16x32_f16 v[36:39], v[162:165], v[194:197], v[36:39]
	v_mfma_f32_16x16x32_f16 v[32:35], v[178:181], v[194:197], v[32:35]
	v_mfma_f32_16x16x32_f16 v[20:23], v[162:165], v[202:205], v[20:23]
	v_mfma_f32_16x16x32_f16 v[16:19], v[178:181], v[202:205], v[16:19]
	v_mfma_f32_16x16x32_f16 v[4:7], v[162:165], v[216:219], v[4:7]
	v_mfma_f32_16x16x32_f16 v[0:3], v[178:181], v[216:219], v[0:3]
	s_setprio 0
	s_barrier
	s_add_u32 s34, s34, 0x100
	s_addc_u32 s35, s35, 0
	s_add_u32 s46, s46, 0x100
	s_addc_u32 s47, s47, 0
	s_cmp_ge_u32 s56, s70
	s_mov_b32 s36, s56
	s_cbranch_scc0 .LBB0_654
	s_branch .Lz654_exit
